# GEMM mainloop heads (three instantiations) aligned to 64-byte boundaries with .p2align, otherwise v13
# speedup vs baseline: 1.0172x; 1.0160x over previous
; template <class Epi>
; DI void gemm_phase(LAS unsigned char* lds, const Gemm g, const StaticOrder& S, const Epi& E) {
;     ...
;   f32x4 acc[2][2][4][2];
; #pragma unroll
;   for (int a = 0; a < 2; ++a)
; #pragma unroll
;     for (int b = 0; b < 2; ++b)
; #pragma unroll
;       for (int m = 0; m < 4; ++m)
; #pragma unroll
;         for (int n = 0; n < 2; ++n) acc[a][b][m][n] = (f32x4){0.f, 0.f, 0.f, 0.f};
.LBB0_327:
	v_mov_b32_e32 v129, 0
	s_andn2_b64 vcc, exec, s[20:21]
	v_mov_b32_e32 v128, v129
	v_mov_b32_e32 v127, v129
	v_mov_b32_e32 v126, v129
	v_mov_b32_e32 v125, v129
	v_mov_b32_e32 v124, v129
	v_mov_b32_e32 v123, v129
	v_mov_b32_e32 v122, v129
	v_mov_b32_e32 v113, v129
	v_mov_b32_e32 v112, v129
	v_mov_b32_e32 v111, v129
	v_mov_b32_e32 v110, v129
	v_mov_b32_e32 v109, v129
	v_mov_b32_e32 v108, v129
	v_mov_b32_e32 v107, v129
	v_mov_b32_e32 v106, v129
	v_mov_b32_e32 v97, v129
	v_mov_b32_e32 v96, v129
	v_mov_b32_e32 v95, v129
	v_mov_b32_e32 v94, v129
	v_mov_b32_e32 v93, v129
	v_mov_b32_e32 v92, v129
	v_mov_b32_e32 v91, v129
	v_mov_b32_e32 v90, v129
	v_mov_b32_e32 v81, v129
	v_mov_b32_e32 v80, v129
	v_mov_b32_e32 v79, v129
	v_mov_b32_e32 v78, v129
	v_mov_b32_e32 v77, v129
	v_mov_b32_e32 v76, v129
	v_mov_b32_e32 v75, v129
	v_mov_b32_e32 v74, v129
	v_mov_b32_e32 v121, v129
	v_mov_b32_e32 v120, v129
	v_mov_b32_e32 v119, v129
	v_mov_b32_e32 v118, v129
	v_mov_b32_e32 v117, v129
	v_mov_b32_e32 v116, v129
	v_mov_b32_e32 v115, v129
	v_mov_b32_e32 v114, v129
	v_mov_b32_e32 v105, v129
	v_mov_b32_e32 v104, v129
	v_mov_b32_e32 v103, v129
	v_mov_b32_e32 v102, v129
	v_mov_b32_e32 v101, v129
	v_mov_b32_e32 v100, v129
	v_mov_b32_e32 v99, v129
	v_mov_b32_e32 v98, v129
	v_mov_b32_e32 v89, v129
	v_mov_b32_e32 v88, v129
	v_mov_b32_e32 v87, v129
	v_mov_b32_e32 v86, v129
	v_mov_b32_e32 v85, v129
	v_mov_b32_e32 v84, v129
	v_mov_b32_e32 v83, v129
	v_mov_b32_e32 v82, v129
	v_mov_b32_e32 v73, v129
	v_mov_b32_e32 v72, v129
	v_mov_b32_e32 v71, v129
	v_mov_b32_e32 v70, v129
	v_mov_b32_e32 v69, v129
	v_mov_b32_e32 v68, v129
	v_mov_b32_e32 v67, v129
	v_mov_b32_e32 v66, v129
	v_mov_b32_e32 v65, v129
	v_mov_b32_e32 v64, v129
	v_mov_b32_e32 v63, v129
	v_mov_b32_e32 v62, v129
	v_mov_b32_e32 v61, v129
	v_mov_b32_e32 v60, v129
	v_mov_b32_e32 v59, v129
	v_mov_b32_e32 v58, v129
	v_mov_b32_e32 v49, v129
	v_mov_b32_e32 v48, v129
	v_mov_b32_e32 v47, v129
	v_mov_b32_e32 v46, v129
	v_mov_b32_e32 v45, v129
	v_mov_b32_e32 v44, v129
	v_mov_b32_e32 v43, v129
	v_mov_b32_e32 v42, v129
	v_mov_b32_e32 v33, v129
	v_mov_b32_e32 v32, v129
	v_mov_b32_e32 v31, v129
	v_mov_b32_e32 v30, v129
	v_mov_b32_e32 v29, v129
	v_mov_b32_e32 v28, v129
	v_mov_b32_e32 v27, v129
	v_mov_b32_e32 v26, v129
	v_mov_b32_e32 v17, v129
	v_mov_b32_e32 v16, v129
	v_mov_b32_e32 v15, v129
	v_mov_b32_e32 v14, v129
	v_mov_b32_e32 v13, v129
	v_mov_b32_e32 v12, v129
	v_mov_b32_e32 v11, v129
	v_mov_b32_e32 v10, v129
	v_mov_b32_e32 v57, v129
	v_mov_b32_e32 v56, v129
	v_mov_b32_e32 v55, v129
	v_mov_b32_e32 v54, v129
	v_mov_b32_e32 v53, v129
	v_mov_b32_e32 v52, v129
	v_mov_b32_e32 v51, v129
	v_mov_b32_e32 v50, v129
	v_mov_b32_e32 v41, v129
	v_mov_b32_e32 v40, v129
	v_mov_b32_e32 v39, v129
	v_mov_b32_e32 v38, v129
	v_mov_b32_e32 v37, v129
	v_mov_b32_e32 v36, v129
	v_mov_b32_e32 v35, v129
	v_mov_b32_e32 v34, v129
	v_mov_b32_e32 v25, v129
	v_mov_b32_e32 v24, v129
	v_mov_b32_e32 v23, v129
	v_mov_b32_e32 v22, v129
	v_mov_b32_e32 v21, v129
	v_mov_b32_e32 v20, v129
	v_mov_b32_e32 v19, v129
	v_mov_b32_e32 v18, v129
	v_mov_b32_e32 v9, v129
	v_mov_b32_e32 v8, v129
	v_mov_b32_e32 v7, v129
	v_mov_b32_e32 v6, v129
	v_mov_b32_e32 v5, v129
	v_mov_b32_e32 v4, v129
	v_mov_b32_e32 v3, v129
	v_mov_b32_e32 v2, v129
	s_cbranch_vccnz .LBB0_330
	s_add_u32 s44, s48, 0x80
	s_addc_u32 s45, s49, 0
	s_add_u32 s48, s46, 0x100
	v_mov_b32_e32 v2, 0
	s_addc_u32 s49, s47, 0
	s_mov_b32 s46, 0
	v_mov_b32_e32 v3, v2
	v_mov_b32_e32 v4, v2
	v_mov_b32_e32 v5, v2
	v_mov_b32_e32 v6, v2
	v_mov_b32_e32 v7, v2
	v_mov_b32_e32 v8, v2
	v_mov_b32_e32 v9, v2
	v_mov_b32_e32 v18, v2
	v_mov_b32_e32 v19, v2
	v_mov_b32_e32 v20, v2
	v_mov_b32_e32 v21, v2
	v_mov_b32_e32 v22, v2
	v_mov_b32_e32 v23, v2
	v_mov_b32_e32 v24, v2
	v_mov_b32_e32 v25, v2
	v_mov_b32_e32 v34, v2
	v_mov_b32_e32 v35, v2
	v_mov_b32_e32 v36, v2
	v_mov_b32_e32 v37, v2
	v_mov_b32_e32 v38, v2
	v_mov_b32_e32 v39, v2
	v_mov_b32_e32 v40, v2
	v_mov_b32_e32 v41, v2
	v_mov_b32_e32 v50, v2
	v_mov_b32_e32 v51, v2
	v_mov_b32_e32 v52, v2
	v_mov_b32_e32 v53, v2
	v_mov_b32_e32 v54, v2
	v_mov_b32_e32 v55, v2
	v_mov_b32_e32 v56, v2
	v_mov_b32_e32 v57, v2
	v_mov_b32_e32 v10, v2
	v_mov_b32_e32 v11, v2
	v_mov_b32_e32 v12, v2
	v_mov_b32_e32 v13, v2
	v_mov_b32_e32 v14, v2
	v_mov_b32_e32 v15, v2
	v_mov_b32_e32 v16, v2
	v_mov_b32_e32 v17, v2
	v_mov_b32_e32 v26, v2
	v_mov_b32_e32 v27, v2
	v_mov_b32_e32 v28, v2
	v_mov_b32_e32 v29, v2
	v_mov_b32_e32 v30, v2
	v_mov_b32_e32 v31, v2
	v_mov_b32_e32 v32, v2
	v_mov_b32_e32 v33, v2
	v_mov_b32_e32 v42, v2
	v_mov_b32_e32 v43, v2
	v_mov_b32_e32 v44, v2
	v_mov_b32_e32 v45, v2
	v_mov_b32_e32 v46, v2
	v_mov_b32_e32 v47, v2
	v_mov_b32_e32 v48, v2
	v_mov_b32_e32 v49, v2
	v_mov_b32_e32 v58, v2
	v_mov_b32_e32 v59, v2
	v_mov_b32_e32 v60, v2
	v_mov_b32_e32 v61, v2
	v_mov_b32_e32 v62, v2
	v_mov_b32_e32 v63, v2
	v_mov_b32_e32 v64, v2
	v_mov_b32_e32 v65, v2
	v_mov_b32_e32 v66, v2
	v_mov_b32_e32 v67, v2
	v_mov_b32_e32 v68, v2
	v_mov_b32_e32 v69, v2
	v_mov_b32_e32 v70, v2
	v_mov_b32_e32 v71, v2
	v_mov_b32_e32 v72, v2
	v_mov_b32_e32 v73, v2
	v_mov_b32_e32 v82, v2
	v_mov_b32_e32 v83, v2
	v_mov_b32_e32 v84, v2
	v_mov_b32_e32 v85, v2
	v_mov_b32_e32 v86, v2
	v_mov_b32_e32 v87, v2
	v_mov_b32_e32 v88, v2
	v_mov_b32_e32 v89, v2
	v_mov_b32_e32 v98, v2
	v_mov_b32_e32 v99, v2
	v_mov_b32_e32 v100, v2
	v_mov_b32_e32 v101, v2
	v_mov_b32_e32 v102, v2
	v_mov_b32_e32 v103, v2
	v_mov_b32_e32 v104, v2
	v_mov_b32_e32 v105, v2
	v_mov_b32_e32 v114, v2
	v_mov_b32_e32 v115, v2
	v_mov_b32_e32 v116, v2
	v_mov_b32_e32 v117, v2
	v_mov_b32_e32 v118, v2
	v_mov_b32_e32 v119, v2
	v_mov_b32_e32 v120, v2
	v_mov_b32_e32 v121, v2
	v_mov_b32_e32 v74, v2
	v_mov_b32_e32 v75, v2
	v_mov_b32_e32 v76, v2
	v_mov_b32_e32 v77, v2
	v_mov_b32_e32 v78, v2
	v_mov_b32_e32 v79, v2
	v_mov_b32_e32 v80, v2
	v_mov_b32_e32 v81, v2
	v_mov_b32_e32 v90, v2
	v_mov_b32_e32 v91, v2
	v_mov_b32_e32 v92, v2
	v_mov_b32_e32 v93, v2
	v_mov_b32_e32 v94, v2
	v_mov_b32_e32 v95, v2
	v_mov_b32_e32 v96, v2
	v_mov_b32_e32 v97, v2
	v_mov_b32_e32 v106, v2
	v_mov_b32_e32 v107, v2
	v_mov_b32_e32 v108, v2
	v_mov_b32_e32 v109, v2
	v_mov_b32_e32 v110, v2
	v_mov_b32_e32 v111, v2
	v_mov_b32_e32 v112, v2
	v_mov_b32_e32 v113, v2
	v_mov_b32_e32 v122, v2
	v_mov_b32_e32 v123, v2
	v_mov_b32_e32 v124, v2
	v_mov_b32_e32 v125, v2
	v_mov_b32_e32 v126, v2
	v_mov_b32_e32 v127, v2
	v_mov_b32_e32 v128, v2
	v_mov_b32_e32 v129, v2
	.p2align	6

; template <class Epi>
; DI void gemm_phase(LAS unsigned char* lds, const Gemm g, const StaticOrder& S, const Epi& E) {
;     ...
;   f32x4 acc[2][2][4][2];
; #pragma unroll
;   for (int a = 0; a < 2; ++a)
; #pragma unroll
;     for (int b = 0; b < 2; ++b)
; #pragma unroll
;       for (int m = 0; m < 4; ++m)
; #pragma unroll
;         for (int n = 0; n < 2; ++n) acc[a][b][m][n] = (f32x4){0.f, 0.f, 0.f, 0.f};
.LBB0_553:
	v_mov_b32_e32 v153, 0
	s_andn2_b64 vcc, exec, s[14:15]
	v_mov_b32_e32 v152, v153
	v_mov_b32_e32 v151, v153
	v_mov_b32_e32 v150, v153
	v_mov_b32_e32 v149, v153
	v_mov_b32_e32 v148, v153
	v_mov_b32_e32 v147, v153
	v_mov_b32_e32 v146, v153
	v_mov_b32_e32 v137, v153
	v_mov_b32_e32 v136, v153
	v_mov_b32_e32 v135, v153
	v_mov_b32_e32 v134, v153
	v_mov_b32_e32 v133, v153
	v_mov_b32_e32 v132, v153
	v_mov_b32_e32 v131, v153
	v_mov_b32_e32 v130, v153
	v_mov_b32_e32 v121, v153
	v_mov_b32_e32 v120, v153
	v_mov_b32_e32 v119, v153
	v_mov_b32_e32 v118, v153
	v_mov_b32_e32 v117, v153
	v_mov_b32_e32 v116, v153
	v_mov_b32_e32 v115, v153
	v_mov_b32_e32 v114, v153
	v_mov_b32_e32 v105, v153
	v_mov_b32_e32 v104, v153
	v_mov_b32_e32 v103, v153
	v_mov_b32_e32 v102, v153
	v_mov_b32_e32 v101, v153
	v_mov_b32_e32 v100, v153
	v_mov_b32_e32 v99, v153
	v_mov_b32_e32 v98, v153
	v_mov_b32_e32 v141, v153
	v_mov_b32_e32 v140, v153
	v_mov_b32_e32 v139, v153
	v_mov_b32_e32 v138, v153
	v_mov_b32_e32 v145, v153
	v_mov_b32_e32 v144, v153
	v_mov_b32_e32 v143, v153
	v_mov_b32_e32 v142, v153
	v_mov_b32_e32 v125, v153
	v_mov_b32_e32 v124, v153
	v_mov_b32_e32 v123, v153
	v_mov_b32_e32 v122, v153
	v_mov_b32_e32 v129, v153
	v_mov_b32_e32 v128, v153
	v_mov_b32_e32 v127, v153
	v_mov_b32_e32 v126, v153
	v_mov_b32_e32 v109, v153
	v_mov_b32_e32 v108, v153
	v_mov_b32_e32 v107, v153
	v_mov_b32_e32 v106, v153
	v_mov_b32_e32 v113, v153
	v_mov_b32_e32 v112, v153
	v_mov_b32_e32 v111, v153
	v_mov_b32_e32 v110, v153
	v_mov_b32_e32 v93, v153
	v_mov_b32_e32 v92, v153
	v_mov_b32_e32 v91, v153
	v_mov_b32_e32 v90, v153
	v_mov_b32_e32 v97, v153
	v_mov_b32_e32 v96, v153
	v_mov_b32_e32 v95, v153
	v_mov_b32_e32 v94, v153
	v_mov_b32_e32 v89, v153
	v_mov_b32_e32 v88, v153
	v_mov_b32_e32 v87, v153
	v_mov_b32_e32 v86, v153
	v_mov_b32_e32 v85, v153
	v_mov_b32_e32 v84, v153
	v_mov_b32_e32 v83, v153
	v_mov_b32_e32 v82, v153
	v_mov_b32_e32 v73, v153
	v_mov_b32_e32 v72, v153
	v_mov_b32_e32 v71, v153
	v_mov_b32_e32 v70, v153
	v_mov_b32_e32 v61, v153
	v_mov_b32_e32 v60, v153
	v_mov_b32_e32 v59, v153
	v_mov_b32_e32 v58, v153
	v_mov_b32_e32 v33, v153
	v_mov_b32_e32 v32, v153
	v_mov_b32_e32 v31, v153
	v_mov_b32_e32 v30, v153
	v_mov_b32_e32 v29, v153
	v_mov_b32_e32 v28, v153
	v_mov_b32_e32 v27, v153
	v_mov_b32_e32 v26, v153
	v_mov_b32_e32 v17, v153
	v_mov_b32_e32 v16, v153
	v_mov_b32_e32 v15, v153
	v_mov_b32_e32 v14, v153
	v_mov_b32_e32 v13, v153
	v_mov_b32_e32 v12, v153
	v_mov_b32_e32 v11, v153
	v_mov_b32_e32 v10, v153
	v_mov_b32_e32 v77, v153
	v_mov_b32_e32 v76, v153
	v_mov_b32_e32 v75, v153
	v_mov_b32_e32 v74, v153
	v_mov_b32_e32 v81, v153
	v_mov_b32_e32 v80, v153
	v_mov_b32_e32 v79, v153
	v_mov_b32_e32 v78, v153
	v_mov_b32_e32 v41, v153
	v_mov_b32_e32 v40, v153
	v_mov_b32_e32 v39, v153
	v_mov_b32_e32 v38, v153
	v_mov_b32_e32 v49, v153
	v_mov_b32_e32 v48, v153
	v_mov_b32_e32 v47, v153
	v_mov_b32_e32 v46, v153
	v_mov_b32_e32 v21, v153
	v_mov_b32_e32 v20, v153
	v_mov_b32_e32 v19, v153
	v_mov_b32_e32 v18, v153
	v_mov_b32_e32 v25, v153
	v_mov_b32_e32 v24, v153
	v_mov_b32_e32 v23, v153
	v_mov_b32_e32 v22, v153
	v_mov_b32_e32 v5, v153
	v_mov_b32_e32 v4, v153
	v_mov_b32_e32 v3, v153
	v_mov_b32_e32 v2, v153
	v_mov_b32_e32 v9, v153
	v_mov_b32_e32 v8, v153
	v_mov_b32_e32 v7, v153
	v_mov_b32_e32 v6, v153
	s_cbranch_vccnz .LBB0_557
	s_add_u32 s42, s62, 0x80
	s_addc_u32 s43, s63, 0
	s_add_u32 s62, s54, 0x100
	v_mov_b32_e32 v6, 0
	s_addc_u32 s63, s55, 0
	s_mov_b32 s54, 0
	v_mov_b32_e32 v7, v6
	v_mov_b32_e32 v8, v6
	v_mov_b32_e32 v9, v6
	v_mov_b32_e32 v2, v6
	v_mov_b32_e32 v3, v6
	v_mov_b32_e32 v4, v6
	v_mov_b32_e32 v5, v6
	v_mov_b32_e32 v22, v6
	v_mov_b32_e32 v23, v6
	v_mov_b32_e32 v24, v6
	v_mov_b32_e32 v25, v6
	v_mov_b32_e32 v18, v6
	v_mov_b32_e32 v19, v6
	v_mov_b32_e32 v20, v6
	v_mov_b32_e32 v21, v6
	v_mov_b32_e32 v46, v6
	v_mov_b32_e32 v47, v6
	v_mov_b32_e32 v48, v6
	v_mov_b32_e32 v49, v6
	v_mov_b32_e32 v38, v6
	v_mov_b32_e32 v39, v6
	v_mov_b32_e32 v40, v6
	v_mov_b32_e32 v41, v6
	v_mov_b32_e32 v78, v6
	v_mov_b32_e32 v79, v6
	v_mov_b32_e32 v80, v6
	v_mov_b32_e32 v81, v6
	v_mov_b32_e32 v74, v6
	v_mov_b32_e32 v75, v6
	v_mov_b32_e32 v76, v6
	v_mov_b32_e32 v77, v6
	v_mov_b32_e32 v10, v6
	v_mov_b32_e32 v11, v6
	v_mov_b32_e32 v12, v6
	v_mov_b32_e32 v13, v6
	v_mov_b32_e32 v14, v6
	v_mov_b32_e32 v15, v6
	v_mov_b32_e32 v16, v6
	v_mov_b32_e32 v17, v6
	v_mov_b32_e32 v26, v6
	v_mov_b32_e32 v27, v6
	v_mov_b32_e32 v28, v6
	v_mov_b32_e32 v29, v6
	v_mov_b32_e32 v30, v6
	v_mov_b32_e32 v31, v6
	v_mov_b32_e32 v32, v6
	v_mov_b32_e32 v33, v6
	v_mov_b32_e32 v58, v6
	v_mov_b32_e32 v59, v6
	v_mov_b32_e32 v60, v6
	v_mov_b32_e32 v61, v6
	v_mov_b32_e32 v70, v6
	v_mov_b32_e32 v71, v6
	v_mov_b32_e32 v72, v6
	v_mov_b32_e32 v73, v6
	v_mov_b32_e32 v82, v6
	v_mov_b32_e32 v83, v6
	v_mov_b32_e32 v84, v6
	v_mov_b32_e32 v85, v6
	v_mov_b32_e32 v86, v6
	v_mov_b32_e32 v87, v6
	v_mov_b32_e32 v88, v6
	v_mov_b32_e32 v89, v6
	v_mov_b32_e32 v94, v6
	v_mov_b32_e32 v95, v6
	v_mov_b32_e32 v96, v6
	v_mov_b32_e32 v97, v6
	v_mov_b32_e32 v90, v6
	v_mov_b32_e32 v91, v6
	v_mov_b32_e32 v92, v6
	v_mov_b32_e32 v93, v6
	v_mov_b32_e32 v110, v6
	v_mov_b32_e32 v111, v6
	v_mov_b32_e32 v112, v6
	v_mov_b32_e32 v113, v6
	v_mov_b32_e32 v106, v6
	v_mov_b32_e32 v107, v6
	v_mov_b32_e32 v108, v6
	v_mov_b32_e32 v109, v6
	v_mov_b32_e32 v126, v6
	v_mov_b32_e32 v127, v6
	v_mov_b32_e32 v128, v6
	v_mov_b32_e32 v129, v6
	v_mov_b32_e32 v122, v6
	v_mov_b32_e32 v123, v6
	v_mov_b32_e32 v124, v6
	v_mov_b32_e32 v125, v6
	v_mov_b32_e32 v142, v6
	v_mov_b32_e32 v143, v6
	v_mov_b32_e32 v144, v6
	v_mov_b32_e32 v145, v6
	v_mov_b32_e32 v138, v6
	v_mov_b32_e32 v139, v6
	v_mov_b32_e32 v140, v6
	v_mov_b32_e32 v141, v6
	v_mov_b32_e32 v98, v6
	v_mov_b32_e32 v99, v6
	v_mov_b32_e32 v100, v6
	v_mov_b32_e32 v101, v6
	v_mov_b32_e32 v102, v6
	v_mov_b32_e32 v103, v6
	v_mov_b32_e32 v104, v6
	v_mov_b32_e32 v105, v6
	v_mov_b32_e32 v114, v6
	v_mov_b32_e32 v115, v6
	v_mov_b32_e32 v116, v6
	v_mov_b32_e32 v117, v6
	v_mov_b32_e32 v118, v6
	v_mov_b32_e32 v119, v6
	v_mov_b32_e32 v120, v6
	v_mov_b32_e32 v121, v6
	v_mov_b32_e32 v130, v6
	v_mov_b32_e32 v131, v6
	v_mov_b32_e32 v132, v6
	v_mov_b32_e32 v133, v6
	v_mov_b32_e32 v134, v6
	v_mov_b32_e32 v135, v6
	v_mov_b32_e32 v136, v6
	v_mov_b32_e32 v137, v6
	v_mov_b32_e32 v146, v6
	v_mov_b32_e32 v147, v6
	v_mov_b32_e32 v148, v6
	v_mov_b32_e32 v149, v6
	v_mov_b32_e32 v150, v6
	v_mov_b32_e32 v151, v6
	v_mov_b32_e32 v152, v6
	v_mov_b32_e32 v153, v6
	.p2align	6

; template <class Epi>
; DI void gemm_phase(LAS unsigned char* lds, const Gemm g, const StaticOrder& S, const Epi& E) {
;     ...
;   f32x4 acc[2][2][4][2];
; #pragma unroll
;   for (int a = 0; a < 2; ++a)
; #pragma unroll
;     for (int b = 0; b < 2; ++b)
; #pragma unroll
;       for (int m = 0; m < 4; ++m)
; #pragma unroll
;         for (int n = 0; n < 2; ++n) acc[a][b][m][n] = (f32x4){0.f, 0.f, 0.f, 0.f};
.LBB0_842:
	v_readlane_b32 s44, v250, 48
	v_mov_b32_e32 v129, 0
	v_readlane_b32 s45, v250, 49
	s_andn2_b64 vcc, exec, s[44:45]
	v_mov_b32_e32 v128, v129
	v_mov_b32_e32 v127, v129
	v_mov_b32_e32 v126, v129
	v_mov_b32_e32 v125, v129
	v_mov_b32_e32 v124, v129
	v_mov_b32_e32 v123, v129
	v_mov_b32_e32 v122, v129
	v_mov_b32_e32 v113, v129
	v_mov_b32_e32 v112, v129
	v_mov_b32_e32 v111, v129
	v_mov_b32_e32 v110, v129
	v_mov_b32_e32 v109, v129
	v_mov_b32_e32 v108, v129
	v_mov_b32_e32 v107, v129
	v_mov_b32_e32 v106, v129
	v_mov_b32_e32 v97, v129
	v_mov_b32_e32 v96, v129
	v_mov_b32_e32 v95, v129
	v_mov_b32_e32 v94, v129
	v_mov_b32_e32 v93, v129
	v_mov_b32_e32 v92, v129
	v_mov_b32_e32 v91, v129
	v_mov_b32_e32 v90, v129
	v_mov_b32_e32 v81, v129
	v_mov_b32_e32 v80, v129
	v_mov_b32_e32 v79, v129
	v_mov_b32_e32 v78, v129
	v_mov_b32_e32 v77, v129
	v_mov_b32_e32 v76, v129
	v_mov_b32_e32 v75, v129
	v_mov_b32_e32 v74, v129
	v_mov_b32_e32 v121, v129
	v_mov_b32_e32 v120, v129
	v_mov_b32_e32 v119, v129
	v_mov_b32_e32 v118, v129
	v_mov_b32_e32 v117, v129
	v_mov_b32_e32 v116, v129
	v_mov_b32_e32 v115, v129
	v_mov_b32_e32 v114, v129
	v_mov_b32_e32 v105, v129
	v_mov_b32_e32 v104, v129
	v_mov_b32_e32 v103, v129
	v_mov_b32_e32 v102, v129
	v_mov_b32_e32 v101, v129
	v_mov_b32_e32 v100, v129
	v_mov_b32_e32 v99, v129
	v_mov_b32_e32 v98, v129
	v_mov_b32_e32 v89, v129
	v_mov_b32_e32 v88, v129
	v_mov_b32_e32 v87, v129
	v_mov_b32_e32 v86, v129
	v_mov_b32_e32 v85, v129
	v_mov_b32_e32 v84, v129
	v_mov_b32_e32 v83, v129
	v_mov_b32_e32 v82, v129
	v_mov_b32_e32 v73, v129
	v_mov_b32_e32 v72, v129
	v_mov_b32_e32 v71, v129
	v_mov_b32_e32 v70, v129
	v_mov_b32_e32 v69, v129
	v_mov_b32_e32 v68, v129
	v_mov_b32_e32 v67, v129
	v_mov_b32_e32 v66, v129
	v_mov_b32_e32 v65, v129
	v_mov_b32_e32 v64, v129
	v_mov_b32_e32 v63, v129
	v_mov_b32_e32 v62, v129
	v_mov_b32_e32 v61, v129
	v_mov_b32_e32 v60, v129
	v_mov_b32_e32 v59, v129
	v_mov_b32_e32 v58, v129
	v_mov_b32_e32 v49, v129
	v_mov_b32_e32 v48, v129
	v_mov_b32_e32 v47, v129
	v_mov_b32_e32 v46, v129
	v_mov_b32_e32 v45, v129
	v_mov_b32_e32 v44, v129
	v_mov_b32_e32 v43, v129
	v_mov_b32_e32 v42, v129
	v_mov_b32_e32 v33, v129
	v_mov_b32_e32 v32, v129
	v_mov_b32_e32 v31, v129
	v_mov_b32_e32 v30, v129
	v_mov_b32_e32 v29, v129
	v_mov_b32_e32 v28, v129
	v_mov_b32_e32 v27, v129
	v_mov_b32_e32 v26, v129
	v_mov_b32_e32 v17, v129
	v_mov_b32_e32 v16, v129
	v_mov_b32_e32 v15, v129
	v_mov_b32_e32 v14, v129
	v_mov_b32_e32 v13, v129
	v_mov_b32_e32 v12, v129
	v_mov_b32_e32 v11, v129
	v_mov_b32_e32 v10, v129
	v_mov_b32_e32 v57, v129
	v_mov_b32_e32 v56, v129
	v_mov_b32_e32 v55, v129
	v_mov_b32_e32 v54, v129
	v_mov_b32_e32 v53, v129
	v_mov_b32_e32 v52, v129
	v_mov_b32_e32 v51, v129
	v_mov_b32_e32 v50, v129
	v_mov_b32_e32 v41, v129
	v_mov_b32_e32 v40, v129
	v_mov_b32_e32 v39, v129
	v_mov_b32_e32 v38, v129
	v_mov_b32_e32 v37, v129
	v_mov_b32_e32 v36, v129
	v_mov_b32_e32 v35, v129
	v_mov_b32_e32 v34, v129
	v_mov_b32_e32 v25, v129
	v_mov_b32_e32 v24, v129
	v_mov_b32_e32 v23, v129
	v_mov_b32_e32 v22, v129
	v_mov_b32_e32 v21, v129
	v_mov_b32_e32 v20, v129
	v_mov_b32_e32 v19, v129
	v_mov_b32_e32 v18, v129
	v_mov_b32_e32 v9, v129
	v_mov_b32_e32 v8, v129
	v_mov_b32_e32 v7, v129
	v_mov_b32_e32 v6, v129
	v_mov_b32_e32 v5, v129
	v_mov_b32_e32 v4, v129
	v_mov_b32_e32 v3, v129
	v_mov_b32_e32 v2, v129
	s_cbranch_vccnz .LBB0_845
	s_add_u32 s44, s48, 0x80
	s_addc_u32 s45, s49, 0
	s_add_u32 s23, s46, 0x100
	v_mov_b32_e32 v2, 0
	s_addc_u32 s48, s47, 0
	s_mov_b32 s46, 0
	v_mov_b32_e32 v3, v2
	v_mov_b32_e32 v4, v2
	v_mov_b32_e32 v5, v2
	v_mov_b32_e32 v6, v2
	v_mov_b32_e32 v7, v2
	v_mov_b32_e32 v8, v2
	v_mov_b32_e32 v9, v2
	v_mov_b32_e32 v18, v2
	v_mov_b32_e32 v19, v2
	v_mov_b32_e32 v20, v2
	v_mov_b32_e32 v21, v2
	v_mov_b32_e32 v22, v2
	v_mov_b32_e32 v23, v2
	v_mov_b32_e32 v24, v2
	v_mov_b32_e32 v25, v2
	v_mov_b32_e32 v34, v2
	v_mov_b32_e32 v35, v2
	v_mov_b32_e32 v36, v2
	v_mov_b32_e32 v37, v2
	v_mov_b32_e32 v38, v2
	v_mov_b32_e32 v39, v2
	v_mov_b32_e32 v40, v2
	v_mov_b32_e32 v41, v2
	v_mov_b32_e32 v50, v2
	v_mov_b32_e32 v51, v2
	v_mov_b32_e32 v52, v2
	v_mov_b32_e32 v53, v2
	v_mov_b32_e32 v54, v2
	v_mov_b32_e32 v55, v2
	v_mov_b32_e32 v56, v2
	v_mov_b32_e32 v57, v2
	v_mov_b32_e32 v10, v2
	v_mov_b32_e32 v11, v2
	v_mov_b32_e32 v12, v2
	v_mov_b32_e32 v13, v2
	v_mov_b32_e32 v14, v2
	v_mov_b32_e32 v15, v2
	v_mov_b32_e32 v16, v2
	v_mov_b32_e32 v17, v2
	v_mov_b32_e32 v26, v2
	v_mov_b32_e32 v27, v2
	v_mov_b32_e32 v28, v2
	v_mov_b32_e32 v29, v2
	v_mov_b32_e32 v30, v2
	v_mov_b32_e32 v31, v2
	v_mov_b32_e32 v32, v2
	v_mov_b32_e32 v33, v2
	v_mov_b32_e32 v42, v2
	v_mov_b32_e32 v43, v2
	v_mov_b32_e32 v44, v2
	v_mov_b32_e32 v45, v2
	v_mov_b32_e32 v46, v2
	v_mov_b32_e32 v47, v2
	v_mov_b32_e32 v48, v2
	v_mov_b32_e32 v49, v2
	v_mov_b32_e32 v58, v2
	v_mov_b32_e32 v59, v2
	v_mov_b32_e32 v60, v2
	v_mov_b32_e32 v61, v2
	v_mov_b32_e32 v62, v2
	v_mov_b32_e32 v63, v2
	v_mov_b32_e32 v64, v2
	v_mov_b32_e32 v65, v2
	v_mov_b32_e32 v66, v2
	v_mov_b32_e32 v67, v2
	v_mov_b32_e32 v68, v2
	v_mov_b32_e32 v69, v2
	v_mov_b32_e32 v70, v2
	v_mov_b32_e32 v71, v2
	v_mov_b32_e32 v72, v2
	v_mov_b32_e32 v73, v2
	v_mov_b32_e32 v82, v2
	v_mov_b32_e32 v83, v2
	v_mov_b32_e32 v84, v2
	v_mov_b32_e32 v85, v2
	v_mov_b32_e32 v86, v2
	v_mov_b32_e32 v87, v2
	v_mov_b32_e32 v88, v2
	v_mov_b32_e32 v89, v2
	v_mov_b32_e32 v98, v2
	v_mov_b32_e32 v99, v2
	v_mov_b32_e32 v100, v2
	v_mov_b32_e32 v101, v2
	v_mov_b32_e32 v102, v2
	v_mov_b32_e32 v103, v2
	v_mov_b32_e32 v104, v2
	v_mov_b32_e32 v105, v2
	v_mov_b32_e32 v114, v2
	v_mov_b32_e32 v115, v2
	v_mov_b32_e32 v116, v2
	v_mov_b32_e32 v117, v2
	v_mov_b32_e32 v118, v2
	v_mov_b32_e32 v119, v2
	v_mov_b32_e32 v120, v2
	v_mov_b32_e32 v121, v2
	v_mov_b32_e32 v74, v2
	v_mov_b32_e32 v75, v2
	v_mov_b32_e32 v76, v2
	v_mov_b32_e32 v77, v2
	v_mov_b32_e32 v78, v2
	v_mov_b32_e32 v79, v2
	v_mov_b32_e32 v80, v2
	v_mov_b32_e32 v81, v2
	v_mov_b32_e32 v90, v2
	v_mov_b32_e32 v91, v2
	v_mov_b32_e32 v92, v2
	v_mov_b32_e32 v93, v2
	v_mov_b32_e32 v94, v2
	v_mov_b32_e32 v95, v2
	v_mov_b32_e32 v96, v2
	v_mov_b32_e32 v97, v2
	v_mov_b32_e32 v106, v2
	v_mov_b32_e32 v107, v2
	v_mov_b32_e32 v108, v2
	v_mov_b32_e32 v109, v2
	v_mov_b32_e32 v110, v2
	v_mov_b32_e32 v111, v2
	v_mov_b32_e32 v112, v2
	v_mov_b32_e32 v113, v2
	v_mov_b32_e32 v122, v2
	v_mov_b32_e32 v123, v2
	v_mov_b32_e32 v124, v2
	v_mov_b32_e32 v125, v2
	v_mov_b32_e32 v126, v2
	v_mov_b32_e32 v127, v2
	v_mov_b32_e32 v128, v2
	v_mov_b32_e32 v129, v2
	.p2align	6
